# G5 epilogue: B fragments take interleaved weight rows so each lane owns two adjacent output columns; one packed bf16x2 dword store per row (full 128-B segments) instead of two 2-byte stores
# speedup vs baseline: 1.0144x; 1.0144x over previous
.LBB0_241:
	s_or_b64 exec, exec, s[0:1]
	v_add_u32_e32 v131, v130, v172
	ds_read_b128 v[132:135], v131
	ds_read_b128 v[142:145], v131 offset:4096
	ds_read_b128 v[146:149], v131 offset:8192
	ds_read_b128 v[150:153], v131 offset:12288
	v_xad_u32 v131, v172, v233, v128
	ds_read_b128 v[154:157], v131 offset:32768
	ds_read_b128 v[158:161], v131 offset:32896
	s_setprio 1
	s_waitcnt lgkmcnt(0)
	v_mfma_f32_32x32x16_bf16 v[112:127], v[132:135], v[154:157], v[112:127]
	v_mfma_f32_32x32x16_bf16 v[96:111], v[132:135], v[158:161], v[96:111]
	v_mfma_f32_32x32x16_bf16 v[80:95], v[142:145], v[154:157], v[80:95]
	v_mfma_f32_32x32x16_bf16 v[64:79], v[142:145], v[158:161], v[64:79]
	v_mfma_f32_32x32x16_bf16 v[48:63], v[146:149], v[154:157], v[48:63]
	v_mfma_f32_32x32x16_bf16 v[32:47], v[146:149], v[158:161], v[32:47]
	v_mfma_f32_32x32x16_bf16 v[16:31], v[150:153], v[154:157], v[16:31]
	v_mfma_f32_32x32x16_bf16 v[0:15], v[150:153], v[158:161], v[0:15]
	s_setprio 0
	v_add_u32_e32 v141, v130, v171
	ds_read_b128 v[130:133], v141
	ds_read_b128 v[134:137], v141 offset:4096
	ds_read_b128 v[142:145], v141 offset:8192
	ds_read_b128 v[146:149], v141 offset:12288
	v_xad_u32 v128, v171, v233, v128
	ds_read_b128 v[150:153], v128 offset:32768
	ds_read_b128 v[154:157], v128 offset:32896
	s_setprio 1
	s_waitcnt lgkmcnt(0)
	v_mfma_f32_32x32x16_bf16 v[112:127], v[130:133], v[150:153], v[112:127]
	v_mfma_f32_32x32x16_bf16 v[96:111], v[130:133], v[154:157], v[96:111]
	v_mfma_f32_32x32x16_bf16 v[80:95], v[134:137], v[150:153], v[80:95]
	v_mfma_f32_32x32x16_bf16 v[64:79], v[134:137], v[154:157], v[64:79]
	v_mfma_f32_32x32x16_bf16 v[48:63], v[142:145], v[150:153], v[48:63]
	v_mfma_f32_32x32x16_bf16 v[32:47], v[142:145], v[154:157], v[32:47]
	v_mfma_f32_32x32x16_bf16 v[16:31], v[146:149], v[150:153], v[16:31]
	v_mfma_f32_32x32x16_bf16 v[0:15], v[146:149], v[154:157], v[0:15]
	s_setprio 0
	v_add_u32_e32 v136, v170, v168
	v_and_b32_e32 v130, 31, v224
	v_and_b32_e32 v131, 0xc0, v224
	v_lshl_or_b32 v130, v130, 1, v131
	v_or_b32_e32 v130, v130, v169
	v_lshlrev_b32_e32 v136, 13, v136
	v_lshl_add_u32 v136, v130, 1, v136
	v_max_f32_e32 v112, v112, v112
	v_max_f32_e32 v96, v96, v96
	v_max_f32_e32 v112, 0, v112
	v_max_f32_e32 v96, 0, v96
	v_mul_f32_e32 v112, v112, v112
	v_mul_f32_e32 v96, v96, v96
	s_mov_b32 s0, s42
	s_mov_b32 s1, s43
	v_cvt_pk_bf16_f32 v112, v112, v96
	global_store_dword v136, v112, s[0:1]
	v_max_f32_e32 v113, v113, v113
	v_max_f32_e32 v97, v97, v97
	v_max_f32_e32 v113, 0, v113
	v_max_f32_e32 v97, 0, v97
	v_mul_f32_e32 v113, v113, v113
	v_mul_f32_e32 v97, v97, v97
	s_add_u32 s0, s42, 0x2000
	s_addc_u32 s1, s43, 0
	v_cvt_pk_bf16_f32 v113, v113, v97
	global_store_dword v136, v113, s[0:1]
	v_max_f32_e32 v114, v114, v114
	v_max_f32_e32 v98, v98, v98
	v_max_f32_e32 v114, 0, v114
	v_max_f32_e32 v98, 0, v98
	v_mul_f32_e32 v114, v114, v114
	v_mul_f32_e32 v98, v98, v98
	s_add_u32 s0, s42, 0x4000
	s_addc_u32 s1, s43, 0
	v_cvt_pk_bf16_f32 v114, v114, v98
	global_store_dword v136, v114, s[0:1]
	v_max_f32_e32 v115, v115, v115
	v_max_f32_e32 v99, v99, v99
	v_max_f32_e32 v115, 0, v115
	v_max_f32_e32 v99, 0, v99
	v_mul_f32_e32 v115, v115, v115
	v_mul_f32_e32 v99, v99, v99
	s_add_u32 s0, s42, 0x6000
	s_addc_u32 s1, s43, 0
	v_cvt_pk_bf16_f32 v115, v115, v99
	global_store_dword v136, v115, s[0:1]
	v_max_f32_e32 v116, v116, v116
	v_max_f32_e32 v100, v100, v100
	v_max_f32_e32 v116, 0, v116
	v_max_f32_e32 v100, 0, v100
	v_mul_f32_e32 v116, v116, v116
	v_mul_f32_e32 v100, v100, v100
	s_add_u32 s0, s42, 0x10000
	s_addc_u32 s1, s43, 0
	v_cvt_pk_bf16_f32 v116, v116, v100
	global_store_dword v136, v116, s[0:1]
	v_max_f32_e32 v117, v117, v117
	v_max_f32_e32 v101, v101, v101
	v_max_f32_e32 v117, 0, v117
	v_max_f32_e32 v101, 0, v101
	v_mul_f32_e32 v117, v117, v117
	v_mul_f32_e32 v101, v101, v101
	s_add_u32 s0, s42, 0x12000
	s_addc_u32 s1, s43, 0
	v_cvt_pk_bf16_f32 v117, v117, v101
	global_store_dword v136, v117, s[0:1]
	v_max_f32_e32 v118, v118, v118
	v_max_f32_e32 v102, v102, v102
	v_max_f32_e32 v118, 0, v118
	v_max_f32_e32 v102, 0, v102
	v_mul_f32_e32 v118, v118, v118
	v_mul_f32_e32 v102, v102, v102
	s_add_u32 s0, s42, 0x14000
	s_addc_u32 s1, s43, 0
	v_cvt_pk_bf16_f32 v118, v118, v102
	global_store_dword v136, v118, s[0:1]
	v_max_f32_e32 v119, v119, v119
	v_max_f32_e32 v103, v103, v103
	v_max_f32_e32 v119, 0, v119
	v_max_f32_e32 v103, 0, v103
	v_mul_f32_e32 v119, v119, v119
	v_mul_f32_e32 v103, v103, v103
	s_add_u32 s0, s42, 0x16000
	s_addc_u32 s1, s43, 0
	v_cvt_pk_bf16_f32 v119, v119, v103
	global_store_dword v136, v119, s[0:1]
	v_max_f32_e32 v120, v120, v120
	v_max_f32_e32 v104, v104, v104
	v_max_f32_e32 v120, 0, v120
	v_max_f32_e32 v104, 0, v104
	v_mul_f32_e32 v120, v120, v120
	v_mul_f32_e32 v104, v104, v104
	s_add_u32 s0, s42, 0x20000
	s_addc_u32 s1, s43, 0
	v_cvt_pk_bf16_f32 v120, v120, v104
	global_store_dword v136, v120, s[0:1]
	v_max_f32_e32 v121, v121, v121
	v_max_f32_e32 v105, v105, v105
	v_max_f32_e32 v121, 0, v121
	v_max_f32_e32 v105, 0, v105
	v_mul_f32_e32 v121, v121, v121
	v_mul_f32_e32 v105, v105, v105
	s_add_u32 s0, s42, 0x22000
	s_addc_u32 s1, s43, 0
	v_cvt_pk_bf16_f32 v121, v121, v105
	global_store_dword v136, v121, s[0:1]
	v_max_f32_e32 v122, v122, v122
	v_max_f32_e32 v106, v106, v106
	v_max_f32_e32 v122, 0, v122
	v_max_f32_e32 v106, 0, v106
	v_mul_f32_e32 v122, v122, v122
	v_mul_f32_e32 v106, v106, v106
	s_add_u32 s0, s42, 0x24000
	s_addc_u32 s1, s43, 0
	v_cvt_pk_bf16_f32 v122, v122, v106
	global_store_dword v136, v122, s[0:1]
	v_max_f32_e32 v123, v123, v123
	v_max_f32_e32 v107, v107, v107
	v_max_f32_e32 v123, 0, v123
	v_max_f32_e32 v107, 0, v107
	v_mul_f32_e32 v123, v123, v123
	v_mul_f32_e32 v107, v107, v107
	s_add_u32 s0, s42, 0x26000
	s_addc_u32 s1, s43, 0
	v_cvt_pk_bf16_f32 v123, v123, v107
	global_store_dword v136, v123, s[0:1]
	v_max_f32_e32 v124, v124, v124
	v_max_f32_e32 v108, v108, v108
	v_max_f32_e32 v124, 0, v124
	v_max_f32_e32 v108, 0, v108
	v_mul_f32_e32 v124, v124, v124
	v_mul_f32_e32 v108, v108, v108
	s_add_u32 s0, s42, 0x30000
	s_addc_u32 s1, s43, 0
	v_cvt_pk_bf16_f32 v124, v124, v108
	global_store_dword v136, v124, s[0:1]
	v_max_f32_e32 v125, v125, v125
	v_max_f32_e32 v109, v109, v109
	v_max_f32_e32 v125, 0, v125
	v_max_f32_e32 v109, 0, v109
	v_mul_f32_e32 v125, v125, v125
	v_mul_f32_e32 v109, v109, v109
	s_add_u32 s0, s42, 0x32000
	s_addc_u32 s1, s43, 0
	v_cvt_pk_bf16_f32 v125, v125, v109
	global_store_dword v136, v125, s[0:1]
	v_max_f32_e32 v126, v126, v126
	v_max_f32_e32 v110, v110, v110
	v_max_f32_e32 v126, 0, v126
	v_max_f32_e32 v110, 0, v110
	v_mul_f32_e32 v126, v126, v126
	v_mul_f32_e32 v110, v110, v110
	s_add_u32 s0, s42, 0x34000
	s_addc_u32 s1, s43, 0
	v_cvt_pk_bf16_f32 v126, v126, v110
	global_store_dword v136, v126, s[0:1]
	v_max_f32_e32 v127, v127, v127
	v_max_f32_e32 v111, v111, v111
	v_max_f32_e32 v127, 0, v127
	v_max_f32_e32 v111, 0, v111
	v_mul_f32_e32 v127, v127, v127
	v_mul_f32_e32 v111, v111, v111
	s_add_u32 s0, s42, 0x36000
	s_addc_u32 s1, s43, 0
	v_cvt_pk_bf16_f32 v127, v127, v111
	global_store_dword v136, v127, s[0:1]
	v_max_f32_e32 v80, v80, v80
	v_max_f32_e32 v64, v64, v64
	v_max_f32_e32 v80, 0, v80
	v_max_f32_e32 v64, 0, v64
	v_mul_f32_e32 v80, v80, v80
	v_mul_f32_e32 v64, v64, v64
	s_add_u32 s0, s42, 0x40000
	s_addc_u32 s1, s43, 0
	v_cvt_pk_bf16_f32 v80, v80, v64
	global_store_dword v136, v80, s[0:1]
	v_max_f32_e32 v81, v81, v81
	v_max_f32_e32 v65, v65, v65
	v_max_f32_e32 v81, 0, v81
	v_max_f32_e32 v65, 0, v65
	v_mul_f32_e32 v81, v81, v81
	v_mul_f32_e32 v65, v65, v65
	s_add_u32 s0, s42, 0x42000
	s_addc_u32 s1, s43, 0
	v_cvt_pk_bf16_f32 v81, v81, v65
	global_store_dword v136, v81, s[0:1]
	v_max_f32_e32 v82, v82, v82
	v_max_f32_e32 v66, v66, v66
	v_max_f32_e32 v82, 0, v82
	v_max_f32_e32 v66, 0, v66
	v_mul_f32_e32 v82, v82, v82
	v_mul_f32_e32 v66, v66, v66
	s_add_u32 s0, s42, 0x44000
	s_addc_u32 s1, s43, 0
	v_cvt_pk_bf16_f32 v82, v82, v66
	global_store_dword v136, v82, s[0:1]
	v_max_f32_e32 v83, v83, v83
	v_max_f32_e32 v67, v67, v67
	v_max_f32_e32 v83, 0, v83
	v_max_f32_e32 v67, 0, v67
	v_mul_f32_e32 v83, v83, v83
	v_mul_f32_e32 v67, v67, v67
	s_add_u32 s0, s42, 0x46000
	s_addc_u32 s1, s43, 0
	v_cvt_pk_bf16_f32 v83, v83, v67
	global_store_dword v136, v83, s[0:1]
	v_max_f32_e32 v84, v84, v84
	v_max_f32_e32 v68, v68, v68
	v_max_f32_e32 v84, 0, v84
	v_max_f32_e32 v68, 0, v68
	v_mul_f32_e32 v84, v84, v84
	v_mul_f32_e32 v68, v68, v68
	s_add_u32 s0, s42, 0x50000
	s_addc_u32 s1, s43, 0
	v_cvt_pk_bf16_f32 v84, v84, v68
	global_store_dword v136, v84, s[0:1]
	v_max_f32_e32 v85, v85, v85
	v_max_f32_e32 v69, v69, v69
	v_max_f32_e32 v85, 0, v85
	v_max_f32_e32 v69, 0, v69
	v_mul_f32_e32 v85, v85, v85
	v_mul_f32_e32 v69, v69, v69
	s_add_u32 s0, s42, 0x52000
	s_addc_u32 s1, s43, 0
	v_cvt_pk_bf16_f32 v85, v85, v69
	global_store_dword v136, v85, s[0:1]
	v_max_f32_e32 v86, v86, v86
	v_max_f32_e32 v70, v70, v70
	v_max_f32_e32 v86, 0, v86
	v_max_f32_e32 v70, 0, v70
	v_mul_f32_e32 v86, v86, v86
	v_mul_f32_e32 v70, v70, v70
	s_add_u32 s0, s42, 0x54000
	s_addc_u32 s1, s43, 0
	v_cvt_pk_bf16_f32 v86, v86, v70
	global_store_dword v136, v86, s[0:1]
	v_max_f32_e32 v87, v87, v87
	v_max_f32_e32 v71, v71, v71
	v_max_f32_e32 v87, 0, v87
	v_max_f32_e32 v71, 0, v71
	v_mul_f32_e32 v87, v87, v87
	v_mul_f32_e32 v71, v71, v71
	s_add_u32 s0, s42, 0x56000
	s_addc_u32 s1, s43, 0
	v_cvt_pk_bf16_f32 v87, v87, v71
	global_store_dword v136, v87, s[0:1]
	v_max_f32_e32 v88, v88, v88
	v_max_f32_e32 v72, v72, v72
	v_max_f32_e32 v88, 0, v88
	v_max_f32_e32 v72, 0, v72
	v_mul_f32_e32 v88, v88, v88
	v_mul_f32_e32 v72, v72, v72
	s_add_u32 s0, s42, 0x60000
	s_addc_u32 s1, s43, 0
	v_cvt_pk_bf16_f32 v88, v88, v72
	global_store_dword v136, v88, s[0:1]
	v_max_f32_e32 v89, v89, v89
	v_max_f32_e32 v73, v73, v73
	v_max_f32_e32 v89, 0, v89
	v_max_f32_e32 v73, 0, v73
	v_mul_f32_e32 v89, v89, v89
	v_mul_f32_e32 v73, v73, v73
	s_add_u32 s0, s42, 0x62000
	s_addc_u32 s1, s43, 0
	v_cvt_pk_bf16_f32 v89, v89, v73
	global_store_dword v136, v89, s[0:1]
	v_max_f32_e32 v90, v90, v90
	v_max_f32_e32 v74, v74, v74
	v_max_f32_e32 v90, 0, v90
	v_max_f32_e32 v74, 0, v74
	v_mul_f32_e32 v90, v90, v90
	v_mul_f32_e32 v74, v74, v74
	s_add_u32 s0, s42, 0x64000
	s_addc_u32 s1, s43, 0
	v_cvt_pk_bf16_f32 v90, v90, v74
	global_store_dword v136, v90, s[0:1]
	v_max_f32_e32 v91, v91, v91
	v_max_f32_e32 v75, v75, v75
	v_max_f32_e32 v91, 0, v91
	v_max_f32_e32 v75, 0, v75
	v_mul_f32_e32 v91, v91, v91
	v_mul_f32_e32 v75, v75, v75
	s_add_u32 s0, s42, 0x66000
	s_addc_u32 s1, s43, 0
	v_cvt_pk_bf16_f32 v91, v91, v75
	global_store_dword v136, v91, s[0:1]
	v_max_f32_e32 v92, v92, v92
	v_max_f32_e32 v76, v76, v76
	v_max_f32_e32 v92, 0, v92
	v_max_f32_e32 v76, 0, v76
	v_mul_f32_e32 v92, v92, v92
	v_mul_f32_e32 v76, v76, v76
	s_add_u32 s0, s42, 0x70000
	s_addc_u32 s1, s43, 0
	v_cvt_pk_bf16_f32 v92, v92, v76
	global_store_dword v136, v92, s[0:1]
	v_max_f32_e32 v93, v93, v93
	v_max_f32_e32 v77, v77, v77
	v_max_f32_e32 v93, 0, v93
	v_max_f32_e32 v77, 0, v77
	v_mul_f32_e32 v93, v93, v93
	v_mul_f32_e32 v77, v77, v77
	s_add_u32 s0, s42, 0x72000
	s_addc_u32 s1, s43, 0
	v_cvt_pk_bf16_f32 v93, v93, v77
	global_store_dword v136, v93, s[0:1]
	v_max_f32_e32 v94, v94, v94
	v_max_f32_e32 v78, v78, v78
	v_max_f32_e32 v94, 0, v94
	v_max_f32_e32 v78, 0, v78
	v_mul_f32_e32 v94, v94, v94
	v_mul_f32_e32 v78, v78, v78
	s_add_u32 s0, s42, 0x74000
	s_addc_u32 s1, s43, 0
	v_cvt_pk_bf16_f32 v94, v94, v78
	global_store_dword v136, v94, s[0:1]
	v_max_f32_e32 v95, v95, v95
	v_max_f32_e32 v79, v79, v79
	v_max_f32_e32 v95, 0, v95
	v_max_f32_e32 v79, 0, v79
	v_mul_f32_e32 v95, v95, v95
	v_mul_f32_e32 v79, v79, v79
	s_add_u32 s0, s42, 0x76000
	s_addc_u32 s1, s43, 0
	v_cvt_pk_bf16_f32 v95, v95, v79
	global_store_dword v136, v95, s[0:1]
	v_max_f32_e32 v48, v48, v48
	v_max_f32_e32 v32, v32, v32
	v_max_f32_e32 v48, 0, v48
	v_max_f32_e32 v32, 0, v32
	v_mul_f32_e32 v48, v48, v48
	v_mul_f32_e32 v32, v32, v32
	s_add_u32 s0, s42, 0x80000
	s_addc_u32 s1, s43, 0
	v_cvt_pk_bf16_f32 v48, v48, v32
	global_store_dword v136, v48, s[0:1]
	v_max_f32_e32 v49, v49, v49
	v_max_f32_e32 v33, v33, v33
	v_max_f32_e32 v49, 0, v49
	v_max_f32_e32 v33, 0, v33
	v_mul_f32_e32 v49, v49, v49
	v_mul_f32_e32 v33, v33, v33
	s_add_u32 s0, s42, 0x82000
	s_addc_u32 s1, s43, 0
	v_cvt_pk_bf16_f32 v49, v49, v33
	global_store_dword v136, v49, s[0:1]
	v_max_f32_e32 v50, v50, v50
	v_max_f32_e32 v34, v34, v34
	v_max_f32_e32 v50, 0, v50
	v_max_f32_e32 v34, 0, v34
	v_mul_f32_e32 v50, v50, v50
	v_mul_f32_e32 v34, v34, v34
	s_add_u32 s0, s42, 0x84000
	s_addc_u32 s1, s43, 0
	v_cvt_pk_bf16_f32 v50, v50, v34
	global_store_dword v136, v50, s[0:1]
	v_max_f32_e32 v51, v51, v51
	v_max_f32_e32 v35, v35, v35
	v_max_f32_e32 v51, 0, v51
	v_max_f32_e32 v35, 0, v35
	v_mul_f32_e32 v51, v51, v51
	v_mul_f32_e32 v35, v35, v35
	s_add_u32 s0, s42, 0x86000
	s_addc_u32 s1, s43, 0
	v_cvt_pk_bf16_f32 v51, v51, v35
	global_store_dword v136, v51, s[0:1]
	v_max_f32_e32 v52, v52, v52
	v_max_f32_e32 v36, v36, v36
	v_max_f32_e32 v52, 0, v52
	v_max_f32_e32 v36, 0, v36
	v_mul_f32_e32 v52, v52, v52
	v_mul_f32_e32 v36, v36, v36
	s_add_u32 s0, s42, 0x90000
	s_addc_u32 s1, s43, 0
	v_cvt_pk_bf16_f32 v52, v52, v36
	global_store_dword v136, v52, s[0:1]
	v_max_f32_e32 v53, v53, v53
	v_max_f32_e32 v37, v37, v37
	v_max_f32_e32 v53, 0, v53
	v_max_f32_e32 v37, 0, v37
	v_mul_f32_e32 v53, v53, v53
	v_mul_f32_e32 v37, v37, v37
	s_add_u32 s0, s42, 0x92000
	s_addc_u32 s1, s43, 0
	v_cvt_pk_bf16_f32 v53, v53, v37
	global_store_dword v136, v53, s[0:1]
	v_max_f32_e32 v54, v54, v54
	v_max_f32_e32 v38, v38, v38
	v_max_f32_e32 v54, 0, v54
	v_max_f32_e32 v38, 0, v38
	v_mul_f32_e32 v54, v54, v54
	v_mul_f32_e32 v38, v38, v38
	s_add_u32 s0, s42, 0x94000
	s_addc_u32 s1, s43, 0
	v_cvt_pk_bf16_f32 v54, v54, v38
	global_store_dword v136, v54, s[0:1]
	v_max_f32_e32 v55, v55, v55
	v_max_f32_e32 v39, v39, v39
	v_max_f32_e32 v55, 0, v55
	v_max_f32_e32 v39, 0, v39
	v_mul_f32_e32 v55, v55, v55
	v_mul_f32_e32 v39, v39, v39
	s_add_u32 s0, s42, 0x96000
	s_addc_u32 s1, s43, 0
	v_cvt_pk_bf16_f32 v55, v55, v39
	global_store_dword v136, v55, s[0:1]
	v_max_f32_e32 v56, v56, v56
	v_max_f32_e32 v40, v40, v40
	v_max_f32_e32 v56, 0, v56
	v_max_f32_e32 v40, 0, v40
	v_mul_f32_e32 v56, v56, v56
	v_mul_f32_e32 v40, v40, v40
	s_add_u32 s0, s42, 0xa0000
	s_addc_u32 s1, s43, 0
	v_cvt_pk_bf16_f32 v56, v56, v40
	global_store_dword v136, v56, s[0:1]
	v_max_f32_e32 v57, v57, v57
	v_max_f32_e32 v41, v41, v41
	v_max_f32_e32 v57, 0, v57
	v_max_f32_e32 v41, 0, v41
	v_mul_f32_e32 v57, v57, v57
	v_mul_f32_e32 v41, v41, v41
	s_add_u32 s0, s42, 0xa2000
	s_addc_u32 s1, s43, 0
	v_cvt_pk_bf16_f32 v57, v57, v41
	global_store_dword v136, v57, s[0:1]
	v_max_f32_e32 v58, v58, v58
	v_max_f32_e32 v42, v42, v42
	v_max_f32_e32 v58, 0, v58
	v_max_f32_e32 v42, 0, v42
	v_mul_f32_e32 v58, v58, v58
	v_mul_f32_e32 v42, v42, v42
	s_add_u32 s0, s42, 0xa4000
	s_addc_u32 s1, s43, 0
	v_cvt_pk_bf16_f32 v58, v58, v42
	global_store_dword v136, v58, s[0:1]
	v_max_f32_e32 v59, v59, v59
	v_max_f32_e32 v43, v43, v43
	v_max_f32_e32 v59, 0, v59
	v_max_f32_e32 v43, 0, v43
	v_mul_f32_e32 v59, v59, v59
	v_mul_f32_e32 v43, v43, v43
	s_add_u32 s0, s42, 0xa6000
	s_addc_u32 s1, s43, 0
	v_cvt_pk_bf16_f32 v59, v59, v43
	global_store_dword v136, v59, s[0:1]
	v_max_f32_e32 v60, v60, v60
	v_max_f32_e32 v44, v44, v44
	v_max_f32_e32 v60, 0, v60
	v_max_f32_e32 v44, 0, v44
	v_mul_f32_e32 v60, v60, v60
	v_mul_f32_e32 v44, v44, v44
	s_add_u32 s0, s42, 0xb0000
	s_addc_u32 s1, s43, 0
	v_cvt_pk_bf16_f32 v60, v60, v44
	global_store_dword v136, v60, s[0:1]
	v_max_f32_e32 v61, v61, v61
	v_max_f32_e32 v45, v45, v45
	v_max_f32_e32 v61, 0, v61
	v_max_f32_e32 v45, 0, v45
	v_mul_f32_e32 v61, v61, v61
	v_mul_f32_e32 v45, v45, v45
	s_add_u32 s0, s42, 0xb2000
	s_addc_u32 s1, s43, 0
	v_cvt_pk_bf16_f32 v61, v61, v45
	global_store_dword v136, v61, s[0:1]
	v_max_f32_e32 v62, v62, v62
	v_max_f32_e32 v46, v46, v46
	v_max_f32_e32 v62, 0, v62
	v_max_f32_e32 v46, 0, v46
	v_mul_f32_e32 v62, v62, v62
	v_mul_f32_e32 v46, v46, v46
	s_add_u32 s0, s42, 0xb4000
	s_addc_u32 s1, s43, 0
	v_cvt_pk_bf16_f32 v62, v62, v46
	global_store_dword v136, v62, s[0:1]
	v_max_f32_e32 v63, v63, v63
	v_max_f32_e32 v47, v47, v47
	v_max_f32_e32 v63, 0, v63
	v_max_f32_e32 v47, 0, v47
	v_mul_f32_e32 v63, v63, v63
	v_mul_f32_e32 v47, v47, v47
	s_add_u32 s0, s42, 0xb6000
	s_addc_u32 s1, s43, 0
	v_cvt_pk_bf16_f32 v63, v63, v47
	global_store_dword v136, v63, s[0:1]
	v_max_f32_e32 v16, v16, v16
	v_max_f32_e32 v0, v0, v0
	v_max_f32_e32 v16, 0, v16
	v_max_f32_e32 v0, 0, v0
	v_mul_f32_e32 v16, v16, v16
	v_mul_f32_e32 v0, v0, v0
	s_add_u32 s0, s42, 0xc0000
	s_addc_u32 s1, s43, 0
	v_cvt_pk_bf16_f32 v16, v16, v0
	global_store_dword v136, v16, s[0:1]
	v_max_f32_e32 v17, v17, v17
	v_max_f32_e32 v1, v1, v1
	v_max_f32_e32 v17, 0, v17
	v_max_f32_e32 v1, 0, v1
	v_mul_f32_e32 v17, v17, v17
	v_mul_f32_e32 v1, v1, v1
	s_add_u32 s0, s42, 0xc2000
	s_addc_u32 s1, s43, 0
	v_cvt_pk_bf16_f32 v17, v17, v1
	global_store_dword v136, v17, s[0:1]
	v_max_f32_e32 v18, v18, v18
	v_max_f32_e32 v2, v2, v2
	v_max_f32_e32 v18, 0, v18
	v_max_f32_e32 v2, 0, v2
	v_mul_f32_e32 v18, v18, v18
	v_mul_f32_e32 v2, v2, v2
	s_add_u32 s0, s42, 0xc4000
	s_addc_u32 s1, s43, 0
	v_cvt_pk_bf16_f32 v18, v18, v2
	global_store_dword v136, v18, s[0:1]
	v_max_f32_e32 v19, v19, v19
	v_max_f32_e32 v3, v3, v3
	v_max_f32_e32 v19, 0, v19
	v_max_f32_e32 v3, 0, v3
	v_mul_f32_e32 v19, v19, v19
	v_mul_f32_e32 v3, v3, v3
	s_add_u32 s0, s42, 0xc6000
	s_addc_u32 s1, s43, 0
	v_cvt_pk_bf16_f32 v19, v19, v3
	global_store_dword v136, v19, s[0:1]
	v_max_f32_e32 v20, v20, v20
	v_max_f32_e32 v4, v4, v4
	v_max_f32_e32 v20, 0, v20
	v_max_f32_e32 v4, 0, v4
	v_mul_f32_e32 v20, v20, v20
	v_mul_f32_e32 v4, v4, v4
	s_add_u32 s0, s42, 0xd0000
	s_addc_u32 s1, s43, 0
	v_cvt_pk_bf16_f32 v20, v20, v4
	global_store_dword v136, v20, s[0:1]
	v_max_f32_e32 v21, v21, v21
	v_max_f32_e32 v5, v5, v5
	v_max_f32_e32 v21, 0, v21
	v_max_f32_e32 v5, 0, v5
	v_mul_f32_e32 v21, v21, v21
	v_mul_f32_e32 v5, v5, v5
	s_add_u32 s0, s42, 0xd2000
	s_addc_u32 s1, s43, 0
	v_cvt_pk_bf16_f32 v21, v21, v5
	global_store_dword v136, v21, s[0:1]
	v_max_f32_e32 v22, v22, v22
	v_max_f32_e32 v6, v6, v6
	v_max_f32_e32 v22, 0, v22
	v_max_f32_e32 v6, 0, v6
	v_mul_f32_e32 v22, v22, v22
	v_mul_f32_e32 v6, v6, v6
	s_add_u32 s0, s42, 0xd4000
	s_addc_u32 s1, s43, 0
	v_cvt_pk_bf16_f32 v22, v22, v6
	global_store_dword v136, v22, s[0:1]
	v_max_f32_e32 v23, v23, v23
	v_max_f32_e32 v7, v7, v7
	v_max_f32_e32 v23, 0, v23
	v_max_f32_e32 v7, 0, v7
	v_mul_f32_e32 v23, v23, v23
	v_mul_f32_e32 v7, v7, v7
	s_add_u32 s0, s42, 0xd6000
	s_addc_u32 s1, s43, 0
	v_cvt_pk_bf16_f32 v23, v23, v7
	global_store_dword v136, v23, s[0:1]
	v_max_f32_e32 v24, v24, v24
	v_max_f32_e32 v8, v8, v8
	v_max_f32_e32 v24, 0, v24
	v_max_f32_e32 v8, 0, v8
	v_mul_f32_e32 v24, v24, v24
	v_mul_f32_e32 v8, v8, v8
	s_add_u32 s0, s42, 0xe0000
	s_addc_u32 s1, s43, 0
	v_cvt_pk_bf16_f32 v24, v24, v8
	global_store_dword v136, v24, s[0:1]
	v_max_f32_e32 v25, v25, v25
	v_max_f32_e32 v9, v9, v9
	v_max_f32_e32 v25, 0, v25
	v_max_f32_e32 v9, 0, v9
	v_mul_f32_e32 v25, v25, v25
	v_mul_f32_e32 v9, v9, v9
	s_add_u32 s0, s42, 0xe2000
	s_addc_u32 s1, s43, 0
	v_cvt_pk_bf16_f32 v25, v25, v9
	global_store_dword v136, v25, s[0:1]
	v_max_f32_e32 v26, v26, v26
	v_max_f32_e32 v10, v10, v10
	v_max_f32_e32 v26, 0, v26
	v_max_f32_e32 v10, 0, v10
	v_mul_f32_e32 v26, v26, v26
	v_mul_f32_e32 v10, v10, v10
	s_add_u32 s0, s42, 0xe4000
	s_addc_u32 s1, s43, 0
	v_cvt_pk_bf16_f32 v26, v26, v10
	global_store_dword v136, v26, s[0:1]
	v_max_f32_e32 v27, v27, v27
	v_max_f32_e32 v11, v11, v11
	v_max_f32_e32 v27, 0, v27
	v_max_f32_e32 v11, 0, v11
	v_mul_f32_e32 v27, v27, v27
	v_mul_f32_e32 v11, v11, v11
	s_add_u32 s0, s42, 0xe6000
	s_addc_u32 s1, s43, 0
	v_cvt_pk_bf16_f32 v27, v27, v11
	global_store_dword v136, v27, s[0:1]
	v_max_f32_e32 v28, v28, v28
	v_max_f32_e32 v12, v12, v12
	v_max_f32_e32 v28, 0, v28
	v_max_f32_e32 v12, 0, v12
	v_mul_f32_e32 v28, v28, v28
	v_mul_f32_e32 v12, v12, v12
	s_add_u32 s0, s42, 0xf0000
	s_addc_u32 s1, s43, 0
	v_cvt_pk_bf16_f32 v28, v28, v12
	global_store_dword v136, v28, s[0:1]
	v_max_f32_e32 v29, v29, v29
	v_max_f32_e32 v13, v13, v13
	v_max_f32_e32 v29, 0, v29
	v_max_f32_e32 v13, 0, v13
	v_mul_f32_e32 v29, v29, v29
	v_mul_f32_e32 v13, v13, v13
	s_add_u32 s0, s42, 0xf2000
	s_addc_u32 s1, s43, 0
	v_cvt_pk_bf16_f32 v29, v29, v13
	global_store_dword v136, v29, s[0:1]
	v_max_f32_e32 v30, v30, v30
	v_max_f32_e32 v14, v14, v14
	v_max_f32_e32 v30, 0, v30
	v_max_f32_e32 v14, 0, v14
	v_mul_f32_e32 v30, v30, v30
	v_mul_f32_e32 v14, v14, v14
	s_add_u32 s0, s42, 0xf4000
	s_addc_u32 s1, s43, 0
	v_cvt_pk_bf16_f32 v30, v30, v14
	global_store_dword v136, v30, s[0:1]
	v_max_f32_e32 v31, v31, v31
	v_max_f32_e32 v15, v15, v15
	v_max_f32_e32 v31, 0, v31
	v_max_f32_e32 v15, 0, v15
	v_mul_f32_e32 v31, v31, v31
	v_mul_f32_e32 v15, v15, v15
	s_add_u32 s0, s42, 0xf6000
	s_addc_u32 s1, s43, 0
	v_cvt_pk_bf16_f32 v31, v31, v15
	global_store_dword v136, v31, s[0:1]
	s_andn2_b64 exec, exec, s[48:49]
	s_cbranch_execz .LBB0_254
.LBB0_242:
	v_mov_b32_e32 v32, v224
	v_mov_b32_e32 v170, v138
	v_and_b32_e32 v0, 31, v32
	v_lshrrev_b32_e32 v1, 1, v32
	v_and_or_b32 v0, v1, s59, v0
	v_lshlrev_b32_e32 v182, 7, v0
	v_lshlrev_b32_e32 v0, 7, v32
	v_and_b32_e32 v183, 0x6000, v0
	v_and_b32_e32 v233, 31, v32
	v_lshl_or_b32 v183, v233, 8, v183
	v_lshrrev_b32_e32 v233, 1, v32
	v_xor_b32_e32 v233, v233, v32
	v_and_b32_e32 v233, 7, v233
	v_lshlrev_b32_e32 v233, 4, v233
	v_lshrrev_b32_e32 v0, 5, v32
	v_bfe_u32 v2, v32, 1, 3
	v_bfe_u32 v1, v32, 5, 1
	v_bitop3_b32 v0, v0, v2, 1 bitop3:0x6c
	v_lshlrev_b32_e32 v184, 4, v0
	v_bitop3_b32 v0, v1, v2, 2 bitop3:0x36
	v_lshlrev_b32_e32 v181, 4, v0
	v_bitop3_b32 v0, v1, v2, 4 bitop3:0x36
	v_ashrrev_i32_e32 v188, 3, v32
	v_add_u32_e32 v3, 0x200, v32
	v_add_u32_e32 v4, 0x400, v32
	v_add_u32_e32 v5, 0x600, v32
	v_lshlrev_b32_e32 v172, 4, v0
	v_bitop3_b32 v0, v1, v2, 6 bitop3:0x36
	v_mov_b32_e32 v169, v140
	s_movk_i32 s0, 0xff
	v_lshrrev_b32_e32 v33, 4, v32
	v_ashrrev_i32_e32 v187, 3, v3
	v_ashrrev_i32_e32 v186, 3, v4
	v_ashrrev_i32_e32 v185, 3, v5
	v_lshrrev_b32_e32 v176, 3, v32
	v_lshrrev_b32_e32 v175, 3, v3
	v_lshrrev_b32_e32 v174, 3, v4
	v_lshrrev_b32_e32 v173, 3, v5
	v_lshlrev_b32_e32 v171, 4, v0
	v_add_u32_e32 v0, v188, v170
	v_cmp_gt_i32_e32 vcc, s73, v32
	v_cmp_lt_i32_e64 s[0:1], s0, v32
	v_xor_b32_e32 v132, v33, v32
	v_lshlrev_b32_e32 v180, 4, v32
	v_lshlrev_b32_e32 v178, 4, v4
	v_ashrrev_i32_e32 v1, 31, v0
	v_add_u32_e32 v2, v187, v170
	v_add_u32_e32 v4, v186, v170
	v_add_u32_e32 v6, v185, v170
	v_add_u32_e32 v8, v176, v170
	v_add_u32_e32 v10, v175, v170
	v_add_u32_e32 v12, v174, v170
	v_add_u32_e32 v14, v173, v170
	v_add_u32_e32 v16, v188, v169
	v_add_u32_e32 v18, v187, v169
	v_add_u32_e32 v20, v186, v169
	v_add_u32_e32 v22, v185, v169
	v_add_u32_e32 v24, v176, v169
	v_add_u32_e32 v26, v175, v169
	v_add_u32_e32 v28, v174, v169
	v_add_u32_e32 v30, v173, v169
	v_bitop3_b32 v32, v33, 7, v32 bitop3:0x48
	v_lshlrev_b32_e32 v179, 4, v3
	v_lshlrev_b32_e32 v177, 4, v5
	v_lshlrev_b64 v[0:1], 11, v[0:1]
	v_ashrrev_i32_e32 v3, 31, v2
	v_ashrrev_i32_e32 v5, 31, v4
	v_ashrrev_i32_e32 v7, 31, v6
	v_ashrrev_i32_e32 v9, 31, v8
	v_ashrrev_i32_e32 v11, 31, v10
	v_ashrrev_i32_e32 v13, 31, v12
	v_ashrrev_i32_e32 v15, 31, v14
	v_ashrrev_i32_e32 v17, 31, v16
	v_ashrrev_i32_e32 v19, 31, v18
	v_ashrrev_i32_e32 v21, 31, v20
	v_ashrrev_i32_e32 v23, 31, v22
	v_ashrrev_i32_e32 v25, 31, v24
	v_ashrrev_i32_e32 v27, 31, v26
	v_ashrrev_i32_e32 v29, 31, v28
	v_ashrrev_i32_e32 v31, 31, v30
	v_lshlrev_b32_e32 v32, 4, v32
	s_waitcnt vmcnt(0)
	v_lshlrev_b64 v[2:3], 11, v[2:3]
	v_lshlrev_b64 v[4:5], 11, v[4:5]
	v_lshlrev_b64 v[6:7], 11, v[6:7]
	v_lshlrev_b64 v[8:9], 11, v[8:9]
	v_lshlrev_b64 v[10:11], 11, v[10:11]
	v_lshlrev_b64 v[12:13], 11, v[12:13]
	v_lshlrev_b64 v[14:15], 11, v[14:15]
	v_lshlrev_b64 v[16:17], 11, v[16:17]
	v_lshlrev_b64 v[18:19], 11, v[18:19]
	v_lshlrev_b64 v[20:21], 11, v[20:21]
	v_lshlrev_b64 v[22:23], 11, v[22:23]
	v_lshlrev_b64 v[24:25], 11, v[24:25]
	v_lshlrev_b64 v[26:27], 11, v[26:27]
	v_lshlrev_b64 v[28:29], 11, v[28:29]
	v_lshlrev_b64 v[30:31], 11, v[30:31]
	v_or_b32_e32 v0, v0, v32
	v_lshl_add_u64 v[134:135], s[44:45], 0, v[0:1]
	v_or_b32_e32 v2, v2, v32
	v_or_b32_e32 v4, v4, v32
	v_or_b32_e32 v6, v6, v32
	v_or_b32_e32 v16, v16, v32
	v_or_b32_e32 v18, v18, v32
	v_or_b32_e32 v20, v20, v32
	v_or_b32_e32 v22, v22, v32
	v_or_b32_e32 v8, v8, v32
	v_or_b32_e32 v10, v10, v32
	v_or_b32_e32 v12, v12, v32
	v_or_b32_e32 v14, v14, v32
	v_or_b32_e32 v24, v24, v32
	v_or_b32_e32 v26, v26, v32
	v_or_b32_e32 v28, v28, v32
	v_or_b32_e32 v30, v30, v32
	v_mov_b32_e32 v0, 0
	v_mov_b32_e32 v128, v139
	v_lshl_add_u64 v[136:137], s[44:45], 0, v[2:3]
	v_lshl_add_u64 v[138:139], s[44:45], 0, v[4:5]
	v_lshl_add_u64 v[140:141], s[44:45], 0, v[6:7]
	v_lshl_add_u64 v[142:143], s[46:47], 0, v[16:17]
	v_lshl_add_u64 v[144:145], s[46:47], 0, v[18:19]
	v_lshl_add_u64 v[146:147], s[46:47], 0, v[20:21]
	v_lshl_add_u64 v[148:149], s[46:47], 0, v[22:23]
	v_lshl_add_u64 v[150:151], s[44:45], 0, v[8:9]
	v_lshl_add_u64 v[152:153], s[44:45], 0, v[10:11]
	v_lshl_add_u64 v[154:155], s[44:45], 0, v[12:13]
	v_lshl_add_u64 v[156:157], s[44:45], 0, v[14:15]
	v_lshl_add_u64 v[158:159], s[46:47], 0, v[24:25]
	v_lshl_add_u64 v[160:161], s[46:47], 0, v[26:27]
	v_lshl_add_u64 v[162:163], s[46:47], 0, v[28:29]
	v_lshl_add_u64 v[164:165], s[46:47], 0, v[30:31]
	s_mov_b64 s[4:5], 0
	v_mov_b32_e32 v1, v0
	v_mov_b32_e32 v2, v0
	v_mov_b32_e32 v3, v0
	v_mov_b32_e32 v4, v0
	v_mov_b32_e32 v5, v0
	v_mov_b32_e32 v6, v0
	v_mov_b32_e32 v7, v0
	v_mov_b32_e32 v8, v0
	v_mov_b32_e32 v9, v0
	v_mov_b32_e32 v10, v0
	v_mov_b32_e32 v11, v0
	v_mov_b32_e32 v12, v0
	v_mov_b32_e32 v13, v0
	v_mov_b32_e32 v14, v0
	v_mov_b32_e32 v15, v0
	v_mov_b32_e32 v16, v0
	v_mov_b32_e32 v17, v0
	v_mov_b32_e32 v18, v0
	v_mov_b32_e32 v19, v0
	v_mov_b32_e32 v20, v0
	v_mov_b32_e32 v21, v0
	v_mov_b32_e32 v22, v0
	v_mov_b32_e32 v23, v0
	v_mov_b32_e32 v24, v0
	v_mov_b32_e32 v25, v0
	v_mov_b32_e32 v26, v0
	v_mov_b32_e32 v27, v0
	v_mov_b32_e32 v28, v0
	v_mov_b32_e32 v29, v0
	v_mov_b32_e32 v30, v0
	v_mov_b32_e32 v31, v0
	v_mov_b32_e32 v32, v0
	v_mov_b32_e32 v33, v0
	v_mov_b32_e32 v34, v0
	v_mov_b32_e32 v35, v0
	v_mov_b32_e32 v36, v0
	v_mov_b32_e32 v37, v0
	v_mov_b32_e32 v38, v0
	v_mov_b32_e32 v39, v0
	v_mov_b32_e32 v40, v0
	v_mov_b32_e32 v41, v0
	v_mov_b32_e32 v42, v0
	v_mov_b32_e32 v43, v0
	v_mov_b32_e32 v44, v0
	v_mov_b32_e32 v45, v0
	v_mov_b32_e32 v46, v0
	v_mov_b32_e32 v47, v0
	v_mov_b32_e32 v48, v0
	v_mov_b32_e32 v49, v0
	v_mov_b32_e32 v50, v0
	v_mov_b32_e32 v51, v0
	v_mov_b32_e32 v52, v0
	v_mov_b32_e32 v53, v0
	v_mov_b32_e32 v54, v0
	v_mov_b32_e32 v55, v0
	v_mov_b32_e32 v56, v0
	v_mov_b32_e32 v57, v0
	v_mov_b32_e32 v58, v0
	v_mov_b32_e32 v59, v0
	v_mov_b32_e32 v60, v0
	v_mov_b32_e32 v61, v0
	v_mov_b32_e32 v62, v0
	v_mov_b32_e32 v63, v0
	v_mov_b32_e32 v64, v0
	v_mov_b32_e32 v65, v0
	v_mov_b32_e32 v66, v0
	v_mov_b32_e32 v67, v0
	v_mov_b32_e32 v68, v0
	v_mov_b32_e32 v69, v0
	v_mov_b32_e32 v70, v0
	v_mov_b32_e32 v71, v0
	v_mov_b32_e32 v72, v0
	v_mov_b32_e32 v73, v0
	v_mov_b32_e32 v74, v0
	v_mov_b32_e32 v75, v0
	v_mov_b32_e32 v76, v0
	v_mov_b32_e32 v77, v0
	v_mov_b32_e32 v78, v0
	v_mov_b32_e32 v79, v0
	v_mov_b32_e32 v80, v0
	v_mov_b32_e32 v81, v0
	v_mov_b32_e32 v82, v0
	v_mov_b32_e32 v83, v0
	v_mov_b32_e32 v84, v0
	v_mov_b32_e32 v85, v0
	v_mov_b32_e32 v86, v0
	v_mov_b32_e32 v87, v0
	v_mov_b32_e32 v88, v0
	v_mov_b32_e32 v89, v0
	v_mov_b32_e32 v90, v0
	v_mov_b32_e32 v91, v0
	v_mov_b32_e32 v92, v0
	v_mov_b32_e32 v93, v0
	v_mov_b32_e32 v94, v0
	v_mov_b32_e32 v95, v0
	v_mov_b32_e32 v96, v0
	v_mov_b32_e32 v97, v0
	v_mov_b32_e32 v98, v0
	v_mov_b32_e32 v99, v0
	v_mov_b32_e32 v100, v0
	v_mov_b32_e32 v101, v0
	v_mov_b32_e32 v102, v0
	v_mov_b32_e32 v103, v0
	v_mov_b32_e32 v104, v0
	v_mov_b32_e32 v105, v0
	v_mov_b32_e32 v106, v0
	v_mov_b32_e32 v107, v0
	v_mov_b32_e32 v108, v0
	v_mov_b32_e32 v109, v0
	v_mov_b32_e32 v110, v0
	v_mov_b32_e32 v111, v0
	v_mov_b32_e32 v112, v0
	v_mov_b32_e32 v113, v0
	v_mov_b32_e32 v114, v0
	v_mov_b32_e32 v115, v0
	v_mov_b32_e32 v116, v0
	v_mov_b32_e32 v117, v0
	v_mov_b32_e32 v118, v0
	v_mov_b32_e32 v119, v0
	v_mov_b32_e32 v120, v0
	v_mov_b32_e32 v121, v0
	v_mov_b32_e32 v122, v0
	v_mov_b32_e32 v123, v0
	v_mov_b32_e32 v124, v0
	v_mov_b32_e32 v125, v0
	v_mov_b32_e32 v126, v0
	v_mov_b32_e32 v127, v0
	s_waitcnt vmcnt(0)
	s_barrier
	s_lshl_b32 s13, s9, 16
	s_and_saveexec_b64 s[6:7], vcc
	s_cbranch_execz .LBB0_245
	s_branch .LBB0_244

.LBB0_245:
	s_or_b64 exec, exec, s[6:7]
	s_add_i32 s6, s13, 0
	v_add_u32_e32 v131, s6, v182
	v_add_u32_e32 v130, s6, v183
	v_add_u32_e32 v133, v131, v184
	v_xad_u32 v230, v184, v233, v130
	ds_read_b128 v[190:193], v133
	ds_read_b128 v[194:197], v133 offset:4096
	ds_read_b128 v[198:201], v133 offset:8192
	ds_read_b128 v[202:205], v133 offset:12288
	ds_read_b128 v[206:209], v230 offset:32768
	ds_read_b128 v[210:213], v230 offset:32896
	v_add_u32_e32 v133, v131, v181
	v_xad_u32 v230, v181, v233, v130
	s_setprio 1
	s_waitcnt lgkmcnt(0)
	v_mfma_f32_32x32x16_bf16 v[112:127], v[190:193], v[206:209], v[112:127]
	ds_read_b128 v[214:217], v133
	v_mfma_f32_32x32x16_bf16 v[96:111], v[190:193], v[210:213], v[96:111]
	ds_read_b128 v[218:221], v133 offset:4096
	v_mfma_f32_32x32x16_bf16 v[80:95], v[194:197], v[206:209], v[80:95]
	ds_read_b128 v[234:237], v133 offset:8192
	v_mfma_f32_32x32x16_bf16 v[64:79], v[194:197], v[210:213], v[64:79]
	ds_read_b128 v[238:241], v133 offset:12288
	v_mfma_f32_32x32x16_bf16 v[48:63], v[198:201], v[206:209], v[48:63]
	ds_read_b128 v[242:245], v230 offset:32768
	v_mfma_f32_32x32x16_bf16 v[32:47], v[198:201], v[210:213], v[32:47]
	ds_read_b128 v[246:249], v230 offset:32896
	v_mfma_f32_32x32x16_bf16 v[16:31], v[202:205], v[206:209], v[16:31]
	v_mfma_f32_32x32x16_bf16 v[0:15], v[202:205], v[210:213], v[0:15]
	s_setprio 0
	v_add_u32_e32 v133, v131, v172
	v_xad_u32 v230, v172, v233, v130
	s_setprio 1
	s_waitcnt lgkmcnt(0)
	v_mfma_f32_32x32x16_bf16 v[112:127], v[214:217], v[242:245], v[112:127]
	ds_read_b128 v[190:193], v133
	v_mfma_f32_32x32x16_bf16 v[96:111], v[214:217], v[246:249], v[96:111]
	ds_read_b128 v[194:197], v133 offset:4096
	v_mfma_f32_32x32x16_bf16 v[80:95], v[218:221], v[242:245], v[80:95]
	ds_read_b128 v[198:201], v133 offset:8192
	v_mfma_f32_32x32x16_bf16 v[64:79], v[218:221], v[246:249], v[64:79]
	ds_read_b128 v[202:205], v133 offset:12288
	v_mfma_f32_32x32x16_bf16 v[48:63], v[234:237], v[242:245], v[48:63]
	ds_read_b128 v[206:209], v230 offset:32768
	v_mfma_f32_32x32x16_bf16 v[32:47], v[234:237], v[246:249], v[32:47]
	ds_read_b128 v[210:213], v230 offset:32896
	v_mfma_f32_32x32x16_bf16 v[16:31], v[238:241], v[242:245], v[16:31]
	v_mfma_f32_32x32x16_bf16 v[0:15], v[238:241], v[246:249], v[0:15]
	s_setprio 0
	s_and_saveexec_b64 s[6:7], s[0:1]
	s_cbranch_execz .LBB0_247
	s_xor_b32 s13, s13, 0x10000
	s_add_i32 s13, s13, 0
	v_add_u32_e32 v133, s13, v180
	v_add_u32_e32 v227, s13, v179
	v_readfirstlane_b32 s14, v133
	v_lshl_add_u64 v[228:229], v[150:151], 0, s[4:5]
	s_mov_b32 m0, s14
	v_readfirstlane_b32 s14, v227
	v_add_u32_e32 v222, s13, v178
	global_load_lds_dwordx4 v[228:229], off
	v_lshl_add_u64 v[228:229], v[152:153], 0, s[4:5]
	s_mov_b32 m0, s14
	v_readfirstlane_b32 s14, v222
	v_add_u32_e32 v223, s13, v177
	global_load_lds_dwordx4 v[228:229], off
	v_lshl_add_u64 v[228:229], v[154:155], 0, s[4:5]
	s_mov_b32 m0, s14
	v_readfirstlane_b32 s13, v223
	v_add_u32_e32 v133, 0x8000, v133
	global_load_lds_dwordx4 v[228:229], off
	v_lshl_add_u64 v[228:229], v[156:157], 0, s[4:5]
	s_mov_b32 m0, s13
	v_readfirstlane_b32 s13, v133
	v_add_u32_e32 v133, 0x8000, v227
	global_load_lds_dwordx4 v[228:229], off
	v_lshl_add_u64 v[228:229], v[158:159], 0, s[4:5]
	s_mov_b32 m0, s13
	v_readfirstlane_b32 s13, v133
	v_add_u32_e32 v133, 0x8000, v222
	global_load_lds_dwordx4 v[228:229], off
	v_lshl_add_u64 v[228:229], v[160:161], 0, s[4:5]
	s_mov_b32 m0, s13
	v_readfirstlane_b32 s13, v133
	v_add_u32_e32 v133, 0x8000, v223
	global_load_lds_dwordx4 v[228:229], off
	v_lshl_add_u64 v[228:229], v[162:163], 0, s[4:5]
	s_mov_b32 m0, s13
	v_readfirstlane_b32 s13, v133
	global_load_lds_dwordx4 v[228:229], off
	v_lshl_add_u64 v[228:229], v[164:165], 0, s[4:5]
	s_mov_b32 m0, s13
	s_nop 0
	global_load_lds_dwordx4 v[228:229], off
.LBB0_247:
	s_or_b64 exec, exec, s[6:7]
	v_add_u32_e32 v133, v131, v171
	v_xad_u32 v230, v171, v233, v130
	s_setprio 1
	s_waitcnt lgkmcnt(0)
	v_mfma_f32_32x32x16_bf16 v[112:127], v[190:193], v[206:209], v[112:127]
	ds_read_b128 v[214:217], v133
	v_mfma_f32_32x32x16_bf16 v[96:111], v[190:193], v[210:213], v[96:111]
	ds_read_b128 v[218:221], v133 offset:4096
	v_mfma_f32_32x32x16_bf16 v[80:95], v[194:197], v[206:209], v[80:95]
	ds_read_b128 v[234:237], v133 offset:8192
	v_mfma_f32_32x32x16_bf16 v[64:79], v[194:197], v[210:213], v[64:79]
	ds_read_b128 v[238:241], v133 offset:12288
	v_mfma_f32_32x32x16_bf16 v[48:63], v[198:201], v[206:209], v[48:63]
	ds_read_b128 v[242:245], v230 offset:32768
	v_mfma_f32_32x32x16_bf16 v[32:47], v[198:201], v[210:213], v[32:47]
	ds_read_b128 v[246:249], v230 offset:32896
	v_mfma_f32_32x32x16_bf16 v[16:31], v[202:205], v[206:209], v[16:31]
	v_mfma_f32_32x32x16_bf16 v[0:15], v[202:205], v[210:213], v[0:15]
	s_setprio 0
	s_setprio 1
	s_waitcnt lgkmcnt(0)
	v_mfma_f32_32x32x16_bf16 v[112:127], v[214:217], v[242:245], v[112:127]
	v_mfma_f32_32x32x16_bf16 v[96:111], v[214:217], v[246:249], v[96:111]
	v_mfma_f32_32x32x16_bf16 v[80:95], v[218:221], v[242:245], v[80:95]
	v_mfma_f32_32x32x16_bf16 v[64:79], v[218:221], v[246:249], v[64:79]
	v_mfma_f32_32x32x16_bf16 v[48:63], v[234:237], v[242:245], v[48:63]
	v_mfma_f32_32x32x16_bf16 v[32:47], v[234:237], v[246:249], v[32:47]
	v_mfma_f32_32x32x16_bf16 v[16:31], v[238:241], v[242:245], v[16:31]
	v_mfma_f32_32x32x16_bf16 v[0:15], v[238:241], v[246:249], v[0:15]
	s_setprio 0
	s_xor_b32 s6, s9, 1
	s_waitcnt vmcnt(0)
	s_add_u32 s4, s4, 0x80
	s_addc_u32 s5, s5, 0
	s_cmpk_lg_i32 s4, 0x780
	s_waitcnt vmcnt(0)
	s_barrier
	s_cbranch_scc1 .LBB0_243
	v_add_u32_e32 v139, s8, v128
	s_movk_i32 s0, 0x5f
	v_cmp_lt_i32_e64 s[0:1], s0, v139
	s_mov_b32 s4, 0x2aaaaaab
	s_nop 0
	v_cndmask_b32_e64 v128, v139, v128, s[0:1]
	v_mul_hi_i32 v130, v128, s4
	v_lshrrev_b32_e32 v131, 31, v130
	v_add_u32_e32 v130, v130, v131
	v_mul_lo_u32 v131, v130, 6
	v_sub_u32_e32 v128, v128, v131
	v_add_lshl_u32 v138, v128, v166, 8
	v_lshlrev_b32_e32 v128, 4, v132
	v_and_b32_e32 v128, 0x70, v128
	s_xor_b64 s[4:5], vcc, -1
	v_lshl_add_u64 v[136:137], s[38:39], 0, v[128:129]
	v_lshl_add_u64 v[134:135], s[40:41], 0, v[128:129]
	v_lshlrev_b32_e32 v140, 8, v130
	s_nor_b64 s[4:5], s[4:5], s[0:1]
	s_and_saveexec_b64 s[14:15], s[4:5]
	s_xor_b64 s[4:5], exec, s[14:15]
	s_cbranch_execz .LBB0_250
	s_lshl_b32 s7, s6, 16
	s_xor_b32 s13, s7, 0x10000
	v_add_u32_e32 v130, v138, v188
	s_add_i32 s13, s13, 0
	v_ashrrev_i32_e32 v131, 31, v130
	v_add_u32_e32 v132, v187, v138
	v_add_u32_e32 v128, s13, v180
	v_lshlrev_b64 v[130:131], 11, v[130:131]
	v_ashrrev_i32_e32 v133, 31, v132
	v_readfirstlane_b32 s14, v128
	v_add_u32_e32 v141, s13, v179
	v_lshlrev_b64 v[132:133], 11, v[132:133]
	v_lshl_add_u64 v[130:131], v[136:137], 0, v[130:131]
	s_mov_b32 m0, s14
	v_readfirstlane_b32 s14, v141
	v_add_u32_e32 v142, v186, v138
	v_lshl_add_u64 v[132:133], v[136:137], 0, v[132:133]
	global_load_lds_dwordx4 v[130:131], off
	s_mov_b32 m0, s14
	v_ashrrev_i32_e32 v143, 31, v142
	v_add_u32_e32 v144, v185, v138
	global_load_lds_dwordx4 v[132:133], off
	v_add_u32_e32 v132, s13, v178
	v_lshlrev_b64 v[142:143], 11, v[142:143]
	v_ashrrev_i32_e32 v145, 31, v144
	v_readfirstlane_b32 s14, v132
	v_add_u32_e32 v133, s13, v177
	v_add_u32_e32 v130, v140, v188
	v_lshlrev_b64 v[144:145], 11, v[144:145]
	v_lshl_add_u64 v[142:143], v[136:137], 0, v[142:143]
	s_mov_b32 m0, s14
	v_readfirstlane_b32 s13, v133
	v_ashrrev_i32_e32 v131, 31, v130
	v_add_u32_e32 v128, 0x8000, v128
	v_lshl_add_u64 v[144:145], v[136:137], 0, v[144:145]
	global_load_lds_dwordx4 v[142:143], off
	s_mov_b32 m0, s13
	v_lshlrev_b64 v[130:131], 11, v[130:131]
	v_readfirstlane_b32 s13, v128
	global_load_lds_dwordx4 v[144:145], off
	v_lshl_add_u64 v[130:131], v[134:135], 0, v[130:131]
	s_mov_b32 m0, s13
	v_add_u32_e32 v128, 0x8000, v141
	global_load_lds_dwordx4 v[130:131], off
	v_add_u32_e32 v130, v187, v140
	v_ashrrev_i32_e32 v131, 31, v130
	v_lshlrev_b64 v[130:131], 11, v[130:131]
	v_readfirstlane_b32 s13, v128
	v_lshl_add_u64 v[130:131], v[134:135], 0, v[130:131]
	s_mov_b32 m0, s13
	v_add_u32_e32 v128, 0x8000, v132
	global_load_lds_dwordx4 v[130:131], off
	v_add_u32_e32 v130, v186, v140
	v_ashrrev_i32_e32 v131, 31, v130
	v_lshlrev_b64 v[130:131], 11, v[130:131]
	v_readfirstlane_b32 s13, v128
	v_lshl_add_u64 v[130:131], v[134:135], 0, v[130:131]
	s_mov_b32 m0, s13
	v_add_u32_e32 v128, 0x8000, v133
	global_load_lds_dwordx4 v[130:131], off
	v_add_u32_e32 v130, v185, v140
	v_ashrrev_i32_e32 v131, 31, v130
	v_lshlrev_b64 v[130:131], 11, v[130:131]
	v_readfirstlane_b32 s13, v128
	v_lshl_add_u64 v[130:131], v[134:135], 0, v[130:131]
	s_mov_b32 m0, s13
	s_nop 0
	global_load_lds_dwordx4 v[130:131], off
.LBB0_250:
	s_or_saveexec_b64 s[4:5], s[4:5]
	v_mov_b32_e32 v131, s7
	s_xor_b64 exec, exec, s[4:5]
	s_lshl_b32 s6, s6, 16
	v_mov_b32_e32 v131, s6
	s_or_b64 exec, exec, s[4:5]
	v_add_u32_e32 v128, 0, v131
	v_add_u32_e32 v130, v128, v182
	v_add_u32_e32 v132, v130, v184
	v_add_u32_e32 v128, v128, v183
	ds_read_b128 v[142:145], v132
	ds_read_b128 v[146:149], v132 offset:4096
	ds_read_b128 v[150:153], v132 offset:8192
	ds_read_b128 v[154:157], v132 offset:12288
	v_xad_u32 v132, v184, v233, v128
	ds_read_b128 v[158:161], v132 offset:32768
	ds_read_b128 v[162:165], v132 offset:32896
	s_and_b64 s[4:5], exec, s[0:1]
	s_or_b64 s[48:49], s[4:5], s[48:49]
	s_setprio 1
	s_waitcnt lgkmcnt(0)
	v_mfma_f32_32x32x16_bf16 v[112:127], v[142:145], v[158:161], v[112:127]
	v_mfma_f32_32x32x16_bf16 v[96:111], v[142:145], v[162:165], v[96:111]
	v_mfma_f32_32x32x16_bf16 v[80:95], v[146:149], v[158:161], v[80:95]
	v_mfma_f32_32x32x16_bf16 v[64:79], v[146:149], v[162:165], v[64:79]
	v_mfma_f32_32x32x16_bf16 v[48:63], v[150:153], v[158:161], v[48:63]
	v_mfma_f32_32x32x16_bf16 v[32:47], v[150:153], v[162:165], v[32:47]
	v_mfma_f32_32x32x16_bf16 v[16:31], v[154:157], v[158:161], v[16:31]
	v_mfma_f32_32x32x16_bf16 v[0:15], v[154:157], v[162:165], v[0:15]
	s_setprio 0
	v_add_u32_e32 v132, v130, v181
	ds_read_b128 v[142:145], v132
	ds_read_b128 v[146:149], v132 offset:4096
	ds_read_b128 v[150:153], v132 offset:8192
	ds_read_b128 v[154:157], v132 offset:12288
	v_xad_u32 v132, v181, v233, v128
	ds_read_b128 v[158:161], v132 offset:32768
	ds_read_b128 v[162:165], v132 offset:32896
	s_setprio 1
	s_waitcnt lgkmcnt(0)
	v_mfma_f32_32x32x16_bf16 v[112:127], v[142:145], v[158:161], v[112:127]
	v_mfma_f32_32x32x16_bf16 v[96:111], v[142:145], v[162:165], v[96:111]
	v_mfma_f32_32x32x16_bf16 v[80:95], v[146:149], v[158:161], v[80:95]
	v_mfma_f32_32x32x16_bf16 v[64:79], v[146:149], v[162:165], v[64:79]
	v_mfma_f32_32x32x16_bf16 v[48:63], v[150:153], v[158:161], v[48:63]
	v_mfma_f32_32x32x16_bf16 v[32:47], v[150:153], v[162:165], v[32:47]
	v_mfma_f32_32x32x16_bf16 v[16:31], v[154:157], v[158:161], v[16:31]
	v_mfma_f32_32x32x16_bf16 v[0:15], v[154:157], v[162:165], v[0:15]
	s_setprio 0
	s_nor_b64 s[4:5], vcc, s[0:1]
	s_and_saveexec_b64 s[0:1], s[4:5]
	s_cbranch_execz .LBB0_241
	v_add_u32_e32 v132, v138, v176
	v_add_u32_e32 v142, v175, v138
	v_add_u32_e32 v144, v174, v138
	v_add_u32_e32 v146, v173, v138
	v_xor_b32_e32 v131, 0x10000, v131
	v_ashrrev_i32_e32 v133, 31, v132
	v_ashrrev_i32_e32 v143, 31, v142
	v_ashrrev_i32_e32 v145, 31, v144
	v_ashrrev_i32_e32 v147, 31, v146
	v_add_u32_e32 v131, 0, v131
	v_lshlrev_b64 v[132:133], 11, v[132:133]
	v_lshlrev_b64 v[142:143], 11, v[142:143]
	v_lshlrev_b64 v[144:145], 11, v[144:145]
	v_lshlrev_b64 v[146:147], 11, v[146:147]
	v_add_u32_e32 v141, v131, v180
	v_lshl_add_u64 v[132:133], v[136:137], 0, v[132:133]
	v_lshl_add_u64 v[142:143], v[136:137], 0, v[142:143]
	v_lshl_add_u64 v[144:145], v[136:137], 0, v[144:145]
	v_lshl_add_u64 v[136:137], v[136:137], 0, v[146:147]
	v_readfirstlane_b32 s4, v141
	v_add_u32_e32 v146, v131, v179
	s_mov_b32 m0, s4
	v_readfirstlane_b32 s4, v146
	global_load_lds_dwordx4 v[132:133], off
	s_mov_b32 m0, s4
	v_add_u32_e32 v132, v140, v176
	global_load_lds_dwordx4 v[142:143], off
	v_add_u32_e32 v142, v131, v178
	v_add_u32_e32 v131, v131, v177
	v_readfirstlane_b32 s4, v142
	s_mov_b32 m0, s4
	v_readfirstlane_b32 s4, v131
	global_load_lds_dwordx4 v[144:145], off
	s_mov_b32 m0, s4
	v_ashrrev_i32_e32 v133, 31, v132
	global_load_lds_dwordx4 v[136:137], off
	v_add_u32_e32 v136, 0x8000, v141
	v_lshlrev_b64 v[132:133], 11, v[132:133]
	v_readfirstlane_b32 s4, v136
	v_lshl_add_u64 v[132:133], v[134:135], 0, v[132:133]
	s_mov_b32 m0, s4
	v_add_u32_e32 v136, 0x8000, v146
	global_load_lds_dwordx4 v[132:133], off
	v_add_u32_e32 v132, v175, v140
	v_ashrrev_i32_e32 v133, 31, v132
	v_lshlrev_b64 v[132:133], 11, v[132:133]
	v_readfirstlane_b32 s4, v136
	v_lshl_add_u64 v[132:133], v[134:135], 0, v[132:133]
	s_mov_b32 m0, s4
	v_add_u32_e32 v136, 0x8000, v142
	global_load_lds_dwordx4 v[132:133], off
	v_add_u32_e32 v132, v174, v140
	v_ashrrev_i32_e32 v133, 31, v132
	v_lshlrev_b64 v[132:133], 11, v[132:133]
	v_readfirstlane_b32 s4, v136
	v_lshl_add_u64 v[132:133], v[134:135], 0, v[132:133]
	s_mov_b32 m0, s4
	v_add_u32_e32 v131, 0x8000, v131
	global_load_lds_dwordx4 v[132:133], off
	v_add_u32_e32 v132, v173, v140
	v_ashrrev_i32_e32 v133, 31, v132
	v_lshlrev_b64 v[132:133], 11, v[132:133]
	v_readfirstlane_b32 s4, v131
	v_lshl_add_u64 v[132:133], v[134:135], 0, v[132:133]
	s_mov_b32 m0, s4
	s_nop 0
	global_load_lds_dwordx4 v[132:133], off
	s_branch .LBB0_241
